# scan split loop tail: four ds_read_b128 -> lgkmcnt(0) -> row-sum blocks now issue their reads together into free VGPR quads with counted waits
# baseline (speedup 1.0000x reference)
; __device__ __forceinline__ unsigned cvt_pk(float lo, float hi) { unsigned r; asm volatile("v_cvt_pk_bf16_f32 %0, %1, %2" : "=v"(r) : "v"(lo), "v"(hi)); return r; }
; template <int SPLIT> __device__ __forceinline__ void scan_item(const Params& p, unsigned char* smem, const int item, const int vh) {
;     ...
;             __syncthreads();
;             const float m_old = sc[0], M127 = sc[1];
;             const float decay = __expf(m_old - M127);
;             {
;                 const f32x4 a4 = *(const f32x4*)(a_s + sp * 4);
;                 float wsv[4];
; #pragma unroll
;                 for (int i = 0; i < 4; ++i) wsv[i] = __expf(a4[i] - M127);
; #pragma unroll
;                 for (int i = 0; i < 4; ++i) { const u32x4 k = kreg[i]; u32x4 w;
;                     w.x = cvt_pk(bflo(k.x) * wsv[i], bfhi(k.x) * wsv[i]); w.y = cvt_pk(bflo(k.y) * wsv[i], bfhi(k.y) * wsv[i]);
;                     w.z = cvt_pk(bflo(k.z) * wsv[i], bfhi(k.z) * wsv[i]); w.w = cvt_pk(bflo(k.w) * wsv[i], bfhi(k.w) * wsv[i]);
;                     *(u32x4*)(KP + swz(sp * 4 + i, ch)) = w; }
; #pragma unroll
;                 for (int e2 = 0; e2 < 4; ++e2) {
;                     const unsigned k0 = kreg[0][e2], k1 = kreg[1][e2], k2 = kreg[2][e2], k3 = kreg[3][e2];
;                     const unsigned v0 = vreg[0][e2], v1 = vreg[1][e2], v2 = vreg[2][e2], v3 = vreg[3][e2];
;                     const int d0 = ch * 8 + 2 * e2, d1 = d0 + 1; const int co = (sp & 1) * 8;
;                     u32x2 o;
;                     o.x = cvt_pk(bflo(k0) * wsv[0], bflo(k1) * wsv[1]); o.y = cvt_pk(bflo(k2) * wsv[2], bflo(k3) * wsv[3]);
;                     *(u32x2*)(KT + swz(d0, sp >> 1) + co) = o;
;                     o.x = cvt_pk(bfhi(k0) * wsv[0], bfhi(k1) * wsv[1]); o.y = cvt_pk(bfhi(k2) * wsv[2], bfhi(k3) * wsv[3]);
;                     *(u32x2*)(KT + swz(d1, sp >> 1) + co) = o;
;                     o.x = (v0 & 0xffffu) | (v1 << 16); o.y = (v2 & 0xffffu) | (v3 << 16);
;                     *(u32x2*)(VT + swz(d0, sp >> 1) + co) = o;
;                     o.x = (v0 >> 16) | (v1 & 0xffff0000u); o.y = (v2 >> 16) | (v3 & 0xffff0000u);
;                     *(u32x2*)(VT + swz(d1, sp >> 1) + co) = o;
;                 }
;             }
;             const size_t rowl = (size_t)(rfirst + rstep * (j * 128 + wid * 16 + li));
.LBB0_316:
	s_or_b64 exec, exec, s[86:87]
	v_mov_b32_e32 v67, s92
	s_waitcnt lgkmcnt(0)
	s_barrier
	ds_read_b64 v[86:87], v67
	ds_read_b128 v[88:91], v98
	s_waitcnt vmcnt(11)
	v_lshlrev_b32_e32 v92, 16, v45
	v_and_b32_e32 v45, 0xffff0000, v45
	v_lshlrev_b32_e32 v94, 16, v46
	v_and_b32_e32 v46, 0xffff0000, v46
	s_waitcnt lgkmcnt(0)
	v_sub_f32_e32 v67, v88, v87
	v_mul_f32_e32 v67, 0x3fb8aa3b, v67
	v_exp_f32_e32 v67, v67
	v_sub_f32_e32 v84, v89, v87
	v_mul_f32_e32 v84, 0x3fb8aa3b, v84
	v_exp_f32_e32 v84, v84
	v_sub_f32_e32 v88, v90, v87
	v_mul_f32_e32 v88, 0x3fb8aa3b, v88
	v_lshlrev_b32_e32 v90, 16, v44
	v_and_b32_e32 v44, 0xffff0000, v44
	v_exp_f32_e32 v88, v88
	v_sub_f32_e32 v89, v91, v87
	v_mul_f32_e32 v90, v67, v90
	v_mul_f32_e32 v91, v67, v44
	v_cvt_pk_bf16_f32 v44, v90, v91
	v_mul_f32_e32 v92, v67, v92
	v_mul_f32_e32 v93, v67, v45
	v_cvt_pk_bf16_f32 v45, v92, v93
	v_mul_f32_e32 v94, v67, v94
	v_mul_f32_e32 v95, v67, v46
	v_cvt_pk_bf16_f32 v46, v94, v95
	v_lshlrev_b32_e32 v151, 16, v47
	v_and_b32_e32 v47, 0xffff0000, v47
	v_mul_f32_e32 v89, 0x3fb8aa3b, v89
	v_mul_f32_e32 v151, v67, v151
	v_mul_f32_e32 v67, v67, v47
	v_cvt_pk_bf16_f32 v47, v151, v67
	ds_write_b128 v133, v[44:47]
	s_waitcnt vmcnt(10)
	v_lshlrev_b32_e32 v44, 16, v40
	v_and_b32_e32 v40, 0xffff0000, v40
	v_lshlrev_b32_e32 v46, 16, v41
	v_and_b32_e32 v41, 0xffff0000, v41
	v_lshlrev_b32_e32 v152, 16, v42
	v_and_b32_e32 v42, 0xffff0000, v42
	v_exp_f32_e32 v89, v89
	v_mul_f32_e32 v44, v84, v44
	v_mul_f32_e32 v45, v84, v40
	v_cvt_pk_bf16_f32 v40, v44, v45
	v_mul_f32_e32 v46, v84, v46
	v_mul_f32_e32 v47, v84, v41
	v_cvt_pk_bf16_f32 v41, v46, v47
	v_mul_f32_e32 v152, v84, v152
	v_mul_f32_e32 v153, v84, v42
	v_cvt_pk_bf16_f32 v42, v152, v153
	v_lshlrev_b32_e32 v154, 16, v43
	v_and_b32_e32 v43, 0xffff0000, v43
	v_mul_f32_e32 v154, v84, v154
	v_mul_f32_e32 v84, v84, v43
	v_cvt_pk_bf16_f32 v43, v154, v84
	ds_write_b128 v134, v[40:43]
	s_waitcnt vmcnt(9)
	v_lshlrev_b32_e32 v40, 16, v36
	v_and_b32_e32 v36, 0xffff0000, v36
	v_lshlrev_b32_e32 v42, 16, v37
	v_and_b32_e32 v37, 0xffff0000, v37
	v_lshlrev_b32_e32 v155, 16, v38
	v_and_b32_e32 v38, 0xffff0000, v38
	v_mul_f32_e32 v40, v88, v40
	v_mul_f32_e32 v41, v88, v36
	v_cvt_pk_bf16_f32 v36, v40, v41
	v_mul_f32_e32 v42, v88, v42
	v_mul_f32_e32 v43, v88, v37
	v_cvt_pk_bf16_f32 v37, v42, v43
	v_mul_f32_e32 v155, v88, v155
	v_mul_f32_e32 v156, v88, v38
	v_cvt_pk_bf16_f32 v38, v155, v156
	v_lshlrev_b32_e32 v157, 16, v39
	v_and_b32_e32 v39, 0xffff0000, v39
	v_mul_f32_e32 v157, v88, v157
	v_mul_f32_e32 v88, v88, v39
	v_cvt_pk_bf16_f32 v39, v157, v88
	ds_write_b128 v135, v[36:39]
	s_waitcnt vmcnt(7)
	v_lshlrev_b32_e32 v36, 16, v32
	v_and_b32_e32 v32, 0xffff0000, v32
	v_lshlrev_b32_e32 v38, 16, v33
	v_and_b32_e32 v33, 0xffff0000, v33
	v_lshlrev_b32_e32 v158, 16, v34
	v_and_b32_e32 v34, 0xffff0000, v34
	v_mul_f32_e32 v36, v89, v36
	v_mul_f32_e32 v37, v89, v32
	v_cvt_pk_bf16_f32 v32, v36, v37
	v_mul_f32_e32 v38, v89, v38
	v_mul_f32_e32 v39, v89, v33
	v_cvt_pk_bf16_f32 v33, v38, v39
	v_mul_f32_e32 v158, v89, v158
	v_mul_f32_e32 v159, v89, v34
	v_cvt_pk_bf16_f32 v34, v158, v159
	v_lshlrev_b32_e32 v160, 16, v35
	v_and_b32_e32 v35, 0xffff0000, v35
	v_mul_f32_e32 v160, v89, v160
	v_mul_f32_e32 v89, v89, v35
	v_cvt_pk_bf16_f32 v35, v160, v89
	ds_write_b128 v136, v[32:35]
	v_cvt_pk_bf16_f32 v32, v90, v44
	v_cvt_pk_bf16_f32 v33, v40, v36
	v_add_u32_e32 v34, v102, v123
	ds_write_b64 v34, v[32:33]
	v_cvt_pk_bf16_f32 v32, v91, v45
	v_cvt_pk_bf16_f32 v33, v41, v37
	v_add_u32_e32 v34, v102, v124
	ds_write_b64 v34, v[32:33]
	s_waitcnt vmcnt(4)
	v_lshlrev_b32_e32 v32, 16, v4
	v_lshlrev_b32_e32 v33, 16, v16
	v_and_or_b32 v32, v0, s95, v32
	v_and_or_b32 v33, v8, s95, v33
	v_add_u32_e32 v34, v103, v123
	v_lshrrev_b32_e32 v0, 16, v0
	ds_write_b64 v34, v[32:33] offset:32768
	v_and_or_b32 v32, v4, s94, v0
	v_lshrrev_b32_e32 v0, 16, v8
	v_and_or_b32 v33, v16, s94, v0
	v_add_u32_e32 v0, v103, v124
	ds_write_b64 v0, v[32:33] offset:32768
	v_add_u32_e32 v0, v102, v125
	v_cvt_pk_bf16_f32 v32, v92, v46
	v_cvt_pk_bf16_f32 v33, v42, v38
	ds_write_b64 v0, v[32:33]
	v_add_u32_e32 v0, v102, v126
	v_cvt_pk_bf16_f32 v32, v93, v47
	v_cvt_pk_bf16_f32 v33, v43, v39
	ds_write_b64 v0, v[32:33]
	v_lshlrev_b32_e32 v0, 16, v5
	v_and_or_b32 v32, v1, s95, v0
	v_lshlrev_b32_e32 v0, 16, v17
	v_and_or_b32 v33, v9, s95, v0
	v_add_u32_e32 v0, v103, v125
	ds_write_b64 v0, v[32:33] offset:32768
	v_lshrrev_b32_e32 v0, 16, v1
	v_lshrrev_b32_e32 v1, 16, v9
	v_and_or_b32 v0, v5, s94, v0
	v_and_or_b32 v1, v17, s94, v1
	v_add_u32_e32 v4, v103, v126
	ds_write_b64 v4, v[0:1] offset:32768
	v_cvt_pk_bf16_f32 v0, v94, v152
	v_cvt_pk_bf16_f32 v1, v155, v158
	v_add_u32_e32 v4, v102, v127
	ds_write_b64 v4, v[0:1]
	v_cvt_pk_bf16_f32 v0, v95, v153
	v_cvt_pk_bf16_f32 v1, v156, v159
	v_add_u32_e32 v4, v102, v128
	ds_write_b64 v4, v[0:1]
	v_lshlrev_b32_e32 v0, 16, v6
	v_lshlrev_b32_e32 v1, 16, v18
	v_and_or_b32 v0, v2, s95, v0
	v_and_or_b32 v1, v10, s95, v1
	v_add_u32_e32 v4, v103, v127
	ds_write_b64 v4, v[0:1] offset:32768
	v_lshrrev_b32_e32 v0, 16, v2
	v_lshrrev_b32_e32 v1, 16, v10
	v_and_or_b32 v0, v6, s94, v0
	v_and_or_b32 v1, v18, s94, v1
	v_add_u32_e32 v2, v103, v128
	ds_write_b64 v2, v[0:1] offset:32768
	v_cvt_pk_bf16_f32 v0, v151, v154
	v_cvt_pk_bf16_f32 v1, v157, v160
	v_add_u32_e32 v2, v102, v129
	ds_write_b64 v2, v[0:1]
	v_cvt_pk_bf16_f32 v0, v67, v84
	v_cvt_pk_bf16_f32 v1, v88, v89
	v_add_u32_e32 v2, v102, v130
	ds_write_b64 v2, v[0:1]
	v_lshlrev_b32_e32 v0, 16, v7
	v_lshlrev_b32_e32 v1, 16, v19
	v_and_or_b32 v0, v3, s95, v0
	v_and_or_b32 v1, v11, s95, v1
	v_add_u32_e32 v2, v103, v129
	ds_write_b64 v2, v[0:1] offset:32768
	v_lshrrev_b32_e32 v0, 16, v3
	v_lshrrev_b32_e32 v1, 16, v11
	v_and_or_b32 v0, v7, s94, v0
	v_and_or_b32 v1, v19, s94, v1
	v_add_u32_e32 v2, v103, v130
	s_lshl_b32 s0, vcc_lo, 7
	ds_write_b64 v2, v[0:1] offset:32768
	v_or_b32_e32 v0, s0, v85
	v_mul_lo_u32 v0, v0, s3
	v_add_u32_e32 v4, s33, v0
	v_ashrrev_i32_e32 v5, 31, v4
	v_lshlrev_b64 v[0:1], 10, v[4:5]
	v_add_u32_e32 v8, s3, v4
	v_lshl_add_u64 v[0:1], v[64:65], 0, v[0:1]
	v_ashrrev_i32_e32 v9, 31, v8
	s_waitcnt lgkmcnt(0)
	s_barrier
; #define SCAN_LOAD(j) do { \
;         _Pragma("unroll") for (int i = 0; i < 4; ++i) { const size_t r = (size_t)(rfirst + rstep * ((j) * 128 + sp * 4 + i)); \
;             kreg[i] = *(const u32x4*)(K0 + r * 512 + h * 128 + ch * 8); vreg[i] = *(const u32x4*)(P0 + r * LDP + 1536 + h * 128 + ch * 8); } \
;         } while (0)
; template <int SPLIT> __device__ __forceinline__ void scan_item(const Params& p, unsigned char* smem, const int item, const int vh) {
;     ...
;             SCAN_LOAD(jn);
;             __builtin_amdgcn_sched_barrier(0);
;             const int l = wid * 16 + li;
;             const float Ml = M_s[l], gl = g_s[l];
;             f32x4 acc[8];
; #pragma unroll
;             for (int nb = 0; nb < 8; ++nb) acc[nb] = (f32x4){0.f, 0.f, 0.f, 0.f};
;             mm16<8>(acc, KP, qf, lane);
	global_load_dwordx4 v[44:47], v[0:1], off
	v_mad_i64_i32 v[0:1], s[4:5], v4, s88, v[80:81]
	v_lshlrev_b64 v[4:5], 10, v[8:9]
	v_add_u32_e32 v16, s3, v8
	v_lshl_add_u64 v[4:5], v[64:65], 0, v[4:5]
	v_ashrrev_i32_e32 v17, 31, v16
	global_load_dwordx4 v[40:43], v[4:5], off
	v_mad_i64_i32 v[4:5], s[4:5], v8, s88, v[80:81]
	v_lshlrev_b64 v[8:9], 10, v[16:17]
	v_lshl_add_u64 v[8:9], v[64:65], 0, v[8:9]
	global_load_dwordx4 v[36:39], v[8:9], off
	v_mad_i64_i32 v[8:9], s[4:5], v16, s88, v[80:81]
	v_add_u32_e32 v16, s3, v16
	v_ashrrev_i32_e32 v17, 31, v16
	v_lshlrev_b64 v[18:19], 10, v[16:17]
	v_lshl_add_u64 v[18:19], v[64:65], 0, v[18:19]
	v_mad_i64_i32 v[16:17], s[4:5], v16, s88, v[80:81]
	global_load_dwordx4 v[0:3], v[0:1], off offset:3072
	v_sub_f32_e32 v67, v86, v87
	global_load_dwordx4 v[4:7], v[4:5], off offset:3072
	v_mul_f32_e32 v67, 0x3fb8aa3b, v67
	global_load_dwordx4 v[8:11], v[8:9], off offset:3072
	v_exp_f32_e32 v84, v67
	global_load_dwordx4 v[32:35], v[18:19], off
	s_nop 0
	global_load_dwordx4 v[16:19], v[16:17], off offset:3072
	v_add_u32_e32 v67, 0, v107
	ds_read_b128 v[88:91], v67
	ds_read_b128 v[92:95], v67 offset:4096
	ds_read_b32 v151, v105
	ds_read_b128 v[152:155], v67 offset:8192
	ds_read_b128 v[156:159], v67 offset:12288
	ds_read_b32 v171, v104
	s_waitcnt vmcnt(11) lgkmcnt(5)
	v_mfma_f32_16x16x32_bf16 v[88:91], v[88:91], v[28:31], 0
	s_waitcnt lgkmcnt(4)
	v_mfma_f32_16x16x32_bf16 v[92:95], v[92:95], v[28:31], 0
	s_waitcnt lgkmcnt(2)
	v_mfma_f32_16x16x32_bf16 v[152:155], v[152:155], v[28:31], 0
	s_waitcnt lgkmcnt(1)
	v_mfma_f32_16x16x32_bf16 v[156:159], v[156:159], v[28:31], 0
	ds_read_b128 v[160:163], v67 offset:16384
	ds_read_b128 v[164:167], v67 offset:20480
	ds_read_b128 v[172:175], v67 offset:24576
	ds_read_b128 v[178:181], v67 offset:28672
	s_waitcnt lgkmcnt(3)
	v_mfma_f32_16x16x32_bf16 v[160:163], v[160:163], v[28:31], 0
	s_waitcnt lgkmcnt(2)
	v_mfma_f32_16x16x32_bf16 v[164:167], v[164:167], v[28:31], 0
	s_waitcnt lgkmcnt(1)
	v_mfma_f32_16x16x32_bf16 v[172:175], v[172:175], v[28:31], 0
	s_waitcnt lgkmcnt(0)
	v_mfma_f32_16x16x32_bf16 v[178:181], v[178:181], v[28:31], 0
	v_add_u32_e32 v246, 0, v109
	ds_read_b128 v[218:221], v246
	ds_read_b128 v[222:225], v246 offset:4096
	ds_read_b128 v[226:229], v246 offset:8192
	ds_read_b128 v[230:233], v246 offset:12288
	ds_read_b128 v[234:237], v246 offset:16384
	v_add_u32_e32 v67, 0, v109
	ds_read_b128 v[238:241], v246 offset:20480
	s_waitcnt vmcnt(10) lgkmcnt(5)
	v_mfma_f32_16x16x32_bf16 v[88:91], v[218:221], v[24:27], v[88:91]
	ds_read_b128 v[218:221], v246 offset:24576
	s_waitcnt lgkmcnt(5)
	v_mfma_f32_16x16x32_bf16 v[92:95], v[222:225], v[24:27], v[92:95]
	ds_read_b128 v[222:225], v246 offset:28672
	s_waitcnt lgkmcnt(5)
	v_mfma_f32_16x16x32_bf16 v[152:155], v[226:229], v[24:27], v[152:155]
	v_add_u32_e32 v247, 0, v111
	ds_read_b128 v[226:229], v247
	s_waitcnt lgkmcnt(5)
	v_mfma_f32_16x16x32_bf16 v[156:159], v[230:233], v[24:27], v[156:159]
	ds_read_b128 v[230:233], v247 offset:4096
	s_waitcnt lgkmcnt(5)
	v_mfma_f32_16x16x32_bf16 v[160:163], v[234:237], v[24:27], v[160:163]
	ds_read_b128 v[234:237], v247 offset:8192
	s_waitcnt lgkmcnt(5)
	v_mfma_f32_16x16x32_bf16 v[164:167], v[238:241], v[24:27], v[164:167]
	ds_read_b128 v[238:241], v247 offset:12288
	s_waitcnt lgkmcnt(5)
	v_mfma_f32_16x16x32_bf16 v[172:175], v[218:221], v[24:27], v[172:175]
	ds_read_b128 v[218:221], v247 offset:16384
	s_waitcnt lgkmcnt(5)
	v_mfma_f32_16x16x32_bf16 v[178:181], v[222:225], v[24:27], v[178:181]
	v_add_u32_e32 v67, 0, v111
	ds_read_b128 v[222:225], v247 offset:20480
	s_waitcnt vmcnt(9) lgkmcnt(5)
	v_mfma_f32_16x16x32_bf16 v[88:91], v[226:229], v[20:23], v[88:91]
	ds_read_b128 v[226:229], v247 offset:24576
	s_waitcnt lgkmcnt(5)
	v_mfma_f32_16x16x32_bf16 v[92:95], v[230:233], v[20:23], v[92:95]
	ds_read_b128 v[230:233], v247 offset:28672
	s_waitcnt lgkmcnt(5)
	v_mfma_f32_16x16x32_bf16 v[152:155], v[234:237], v[20:23], v[152:155]
	v_add_u32_e32 v248, 0, v113
	ds_read_b128 v[234:237], v248
	s_waitcnt lgkmcnt(5)
	v_mfma_f32_16x16x32_bf16 v[156:159], v[238:241], v[20:23], v[156:159]
	ds_read_b128 v[238:241], v248 offset:4096
	s_waitcnt lgkmcnt(5)
	v_mfma_f32_16x16x32_bf16 v[160:163], v[218:221], v[20:23], v[160:163]
	ds_read_b128 v[218:221], v248 offset:8192
	s_waitcnt lgkmcnt(5)
	v_mfma_f32_16x16x32_bf16 v[164:167], v[222:225], v[20:23], v[164:167]
	ds_read_b128 v[222:225], v248 offset:12288
	s_waitcnt lgkmcnt(5)
	v_mfma_f32_16x16x32_bf16 v[172:175], v[226:229], v[20:23], v[172:175]
	ds_read_b128 v[226:229], v248 offset:16384
	s_waitcnt lgkmcnt(5)
	v_mfma_f32_16x16x32_bf16 v[178:181], v[230:233], v[20:23], v[178:181]
	v_add_u32_e32 v67, 0, v113
	ds_read_b128 v[230:233], v248 offset:20480
	s_waitcnt vmcnt(8) lgkmcnt(5)
	v_mfma_f32_16x16x32_bf16 v[88:91], v[234:237], v[12:15], v[88:91]
	ds_read_b128 v[234:237], v248 offset:24576
	s_waitcnt lgkmcnt(5)
	v_mfma_f32_16x16x32_bf16 v[92:95], v[238:241], v[12:15], v[92:95]
	ds_read_b128 v[238:241], v248 offset:28672
	s_waitcnt lgkmcnt(5)
	v_mfma_f32_16x16x32_bf16 v[152:155], v[218:221], v[12:15], v[152:155]
	s_nop 0
	s_waitcnt lgkmcnt(4)
	v_mfma_f32_16x16x32_bf16 v[156:159], v[222:225], v[12:15], v[156:159]
	s_nop 0
	s_waitcnt lgkmcnt(3)
	v_mfma_f32_16x16x32_bf16 v[160:163], v[226:229], v[12:15], v[160:163]
	s_nop 0
	s_waitcnt lgkmcnt(2)
	v_mfma_f32_16x16x32_bf16 v[164:167], v[230:233], v[12:15], v[164:167]
	s_nop 0
	s_waitcnt lgkmcnt(1)
	v_mfma_f32_16x16x32_bf16 v[172:175], v[234:237], v[12:15], v[172:175]
	s_nop 0
	s_waitcnt lgkmcnt(0)
	v_mfma_f32_16x16x32_bf16 v[178:181], v[238:241], v[12:15], v[178:181]
	v_mov_b32_e32 v67, s6
	ds_read_b32 v67, v67
	s_waitcnt lgkmcnt(0)
; __device__ __forceinline__ unsigned cvt_pk(float lo, float hi) { unsigned r; asm volatile("v_cvt_pk_bf16_f32 %0, %1, %2" : "=v"(r) : "v"(lo), "v"(hi)); return r; }
; __device__ __forceinline__ float bflo(unsigned w) { return __uint_as_float(w << 16); }
; __device__ __forceinline__ float bfhi(unsigned w) { return __uint_as_float(w & 0xffff0000u); }
; template <int SPLIT> __device__ __forceinline__ void scan_item(const Params& p, unsigned char* smem, const int item, const int vh) {
;     ...
;             float rs = 0.f; u32x2 pp[8];
;             const float rowf = __expf(fminf(sc[1] - Ml, 80.f));
; #pragma unroll
;             for (int nb = 0; nb < 8; ++nb) { float pv[4];
; #pragma unroll
;                 for (int jj = 0; jj < 4; ++jj) { const int s = nb * 16 + kq * 4 + jj; pv[jj] = (s <= l) ? acc[nb][jj] * rowf : 0.f; rs += pv[jj]; }
;                 pp[nb].x = cvt_pk(pv[0], pv[1]); pp[nb].y = cvt_pk(pv[2], pv[3]); }
;             __builtin_amdgcn_sched_barrier(0);
;             float nq = 0.f;
; #pragma unroll
;             for (int ks = 0; ks < 4; ++ks) { const f32x4 n0 = *(const f32x4*)(n_s + ks * 32 + kq * 8), n1 = *(const f32x4*)(n_s + ks * 32 + kq * 8 + 4);
;                 const u32x4 qw = *(const u32x4*)&qf[ks];
;                 nq += bflo(qw.x) * n0[0] + bfhi(qw.x) * n0[1] + bflo(qw.y) * n0[2] + bfhi(qw.y) * n0[3] + bflo(qw.z) * n1[0] + bfhi(qw.z) * n1[1] + bflo(qw.w) * n1[2] + bfhi(qw.w) * n1[3]; }
	v_sub_f32_e32 v67, v67, v171
	v_min_f32_e32 v67, 0x42a00000, v67
	v_mul_f32_e32 v67, 0x3fb8aa3b, v67
	v_exp_f32_e32 v87, v67
	s_nop 0
	v_mul_f32_e32 v67, v88, v87
	v_mul_f32_e32 v88, v89, v87
	v_cndmask_b32_e64 v67, v67, 0, s[10:11]
	v_mul_f32_e32 v89, v90, v87
	v_mul_f32_e32 v90, v91, v87
	v_cndmask_b32_e64 v91, 0, v88, s[12:13]
	v_add_f32_e32 v168, 0, v67
	v_cndmask_b32_e64 v89, v89, 0, s[14:15]
	v_cvt_pk_bf16_f32 v88, v67, v91
	v_add_f32_e32 v67, v91, v168
	v_cndmask_b32_e64 v90, v90, 0, s[16:17]
	v_add_f32_e32 v67, v89, v67
	v_add_f32_e32 v67, v90, v67
	v_cvt_pk_bf16_f32 v89, v89, v90
	v_mul_f32_e32 v90, v92, v87
	v_cndmask_b32_e64 v90, v90, 0, s[18:19]
	v_mul_f32_e32 v91, v93, v87
	v_add_f32_e32 v67, v90, v67
	v_cndmask_b32_e64 v91, v91, 0, s[20:21]
	v_mul_f32_e32 v92, v94, v87
	v_add_f32_e32 v67, v91, v67
	v_cndmask_b32_e64 v92, v92, 0, s[22:23]
	v_mul_f32_e32 v93, v95, v87
	v_add_f32_e32 v67, v92, v67
	v_cndmask_b32_e64 v93, v93, 0, s[24:25]
	v_cvt_pk_bf16_f32 v90, v90, v91
	v_cvt_pk_bf16_f32 v91, v92, v93
	v_mul_f32_e32 v92, v152, v87
	v_add_f32_e32 v67, v93, v67
	v_cndmask_b32_e64 v92, v92, 0, s[26:27]
	v_mul_f32_e32 v93, v153, v87
	v_add_f32_e32 v67, v92, v67
	v_cndmask_b32_e64 v93, v93, 0, s[28:29]
	v_mul_f32_e32 v94, v154, v87
	v_add_f32_e32 v67, v93, v67
	v_cndmask_b32_e64 v94, v94, 0, s[30:31]
	v_mul_f32_e32 v95, v155, v87
	v_add_f32_e32 v67, v94, v67
	v_cndmask_b32_e64 v95, v95, 0, s[34:35]
	v_cvt_pk_bf16_f32 v92, v92, v93
	v_cvt_pk_bf16_f32 v93, v94, v95
	v_mul_f32_e32 v94, v156, v87
	v_add_f32_e32 v67, v95, v67
	v_cndmask_b32_e64 v94, v94, 0, s[36:37]
	v_mul_f32_e32 v95, v157, v87
	v_add_f32_e32 v67, v94, v67
	v_cndmask_b32_e64 v95, v95, 0, s[38:39]
	v_mul_f32_e32 v152, v158, v87
	v_add_f32_e32 v67, v95, v67
	v_cndmask_b32_e64 v152, v152, 0, s[40:41]
	v_mul_f32_e32 v153, v159, v87
	v_add_f32_e32 v67, v152, v67
	v_cndmask_b32_e64 v153, v153, 0, s[42:43]
	v_cvt_pk_bf16_f32 v94, v94, v95
	v_cvt_pk_bf16_f32 v95, v152, v153
	v_mul_f32_e32 v152, v160, v87
	v_add_f32_e32 v67, v153, v67
	v_cndmask_b32_e64 v152, v152, 0, s[44:45]
	v_mul_f32_e32 v153, v161, v87
	v_add_f32_e32 v67, v152, v67
	v_cndmask_b32_e64 v153, v153, 0, s[46:47]
	v_mul_f32_e32 v154, v162, v87
	v_add_f32_e32 v67, v153, v67
	v_cndmask_b32_e64 v154, v154, 0, s[48:49]
	v_mul_f32_e32 v155, v163, v87
	v_add_f32_e32 v67, v154, v67
	v_cndmask_b32_e64 v155, v155, 0, s[50:51]
	v_cvt_pk_bf16_f32 v168, v152, v153
	v_mul_f32_e32 v152, v164, v87
	v_add_f32_e32 v67, v155, v67
	v_cndmask_b32_e64 v152, v152, 0, s[52:53]
	v_add_f32_e32 v161, v152, v67
	v_mul_f32_e32 v67, v165, v87
	v_cndmask_b32_e64 v163, v67, 0, s[54:55]
	v_mul_f32_e32 v67, v166, v87
	v_cndmask_b32_e64 v183, v67, 0, s[56:57]
	v_mul_f32_e32 v67, v167, v87
	v_cndmask_b32_e64 v185, v67, 0, s[58:59]
	v_mul_f32_e32 v67, v172, v87
	v_cndmask_b32_e64 v189, v67, 0, s[60:61]
	v_mul_f32_e32 v67, v173, v87
	v_cndmask_b32_e64 v173, v67, 0, s[62:63]
	v_mul_f32_e32 v67, v174, v87
	v_cndmask_b32_e64 v191, v67, 0, s[64:65]
	v_mul_f32_e32 v67, v175, v87
	v_cvt_pk_bf16_f32 v169, v154, v155
	v_cvt_pk_bf16_f32 v186, v152, v163
	v_cndmask_b32_e64 v175, v67, 0, s[66:67]
	v_mul_f32_e32 v67, v178, v87
	v_mul_f32_e32 v152, v179, v87
	v_cndmask_b32_e64 v67, v67, 0, s[68:69]
	v_cndmask_b32_e64 v177, v152, 0, s[70:71]
	v_mul_f32_e32 v152, v180, v87
	v_mul_f32_e32 v87, v181, v87
	v_cvt_pk_bf16_f32 v187, v183, v185
	v_cvt_pk_bf16_f32 v192, v189, v173
	v_cvt_pk_bf16_f32 v193, v191, v175
	v_cndmask_b32_e64 v200, v152, 0, s[72:73]
	v_cndmask_b32_e64 v201, v87, 0, s[74:75]
	v_cvt_pk_bf16_f32 v178, v67, v177
	v_cvt_pk_bf16_f32 v179, v200, v201
	ds_read_b128 v[152:155], v137
	ds_read_b128 v[156:159], v137 offset:16
	v_lshlrev_b32_e32 v87, 16, v28
	v_and_b32_e32 v160, 0xffff0000, v28
	v_and_b32_e32 v195, 0xffff0000, v27
	s_waitcnt lgkmcnt(1)
	v_mul_f32_e32 v162, v152, v87
	v_lshlrev_b32_e32 v87, 16, v29
	v_mul_f32_e32 v182, v154, v87
	v_and_b32_e32 v87, 0xffff0000, v29
	v_mul_f32_e32 v160, v153, v160
	v_mul_f32_e32 v184, v155, v87
	v_lshlrev_b32_e32 v87, 16, v30
	ds_read_b128 v[152:155], v137 offset:128
	s_waitcnt lgkmcnt(1)
	v_mul_f32_e32 v188, v156, v87
	v_and_b32_e32 v87, 0xffff0000, v30
	v_mul_f32_e32 v172, v157, v87
	v_lshlrev_b32_e32 v87, 16, v31
	v_mul_f32_e32 v190, v158, v87
	v_and_b32_e32 v87, 0xffff0000, v31
	v_pk_add_f32 v[180:181], v[162:163], v[160:161]
	v_mul_f32_e32 v174, v159, v87
	ds_read_b128 v[156:159], v137 offset:144
	v_and_b32_e32 v161, 0xffff0000, v24
	v_lshlrev_b32_e32 v160, 16, v24
	s_waitcnt lgkmcnt(1)
	v_mul_f32_e32 v162, v153, v161
	v_pk_fma_f32 v[152:153], v[152:153], v[160:161], v[162:163] op_sel_hi:[1,1,0]
	v_and_b32_e32 v161, 0xffff0000, v25
	v_lshlrev_b32_e32 v160, 16, v25
	v_pk_fma_f32 v[152:153], v[154:155], v[160:161], v[152:153]
	v_mul_f32_e32 v154, v155, v161
	v_pk_add_f32 v[152:153], v[154:155], v[152:153] op_sel_hi:[0,1]
	v_and_b32_e32 v155, 0xffff0000, v26
	v_lshlrev_b32_e32 v154, 16, v26
	s_waitcnt lgkmcnt(0)
	v_pk_fma_f32 v[152:153], v[156:157], v[154:155], v[152:153]
	v_mul_f32_e32 v154, v157, v155
	v_pk_add_f32 v[156:157], v[154:155], v[152:153] op_sel_hi:[0,1]
	ds_read_b128 v[152:155], v137 offset:256
	ds_read_b128 v[160:163], v137 offset:272
	v_lshlrev_b32_e32 v194, 16, v27
	v_and_b32_e32 v165, 0xffff0000, v20
	v_pk_fma_f32 v[156:157], v[158:159], v[194:195], v[156:157]
	v_lshlrev_b32_e32 v164, 16, v20
	s_waitcnt lgkmcnt(1)
	v_mul_f32_e32 v158, v153, v165
	v_pk_fma_f32 v[152:153], v[152:153], v[164:165], v[158:159] op_sel_hi:[1,1,0]
	v_and_b32_e32 v165, 0xffff0000, v21
	v_lshlrev_b32_e32 v164, 16, v21
	v_pk_fma_f32 v[152:153], v[154:155], v[164:165], v[152:153]
	v_mul_f32_e32 v154, v155, v165
	v_pk_add_f32 v[152:153], v[154:155], v[152:153] op_sel_hi:[0,1]
	v_and_b32_e32 v155, 0xffff0000, v22
	v_lshlrev_b32_e32 v154, 16, v22
	s_waitcnt lgkmcnt(0)
; __device__ __forceinline__ float bflo(unsigned w) { return __uint_as_float(w << 16); }
; __device__ __forceinline__ float bfhi(unsigned w) { return __uint_as_float(w & 0xffff0000u); }
; template <int SPLIT> __device__ __forceinline__ void scan_item(const Params& p, unsigned char* smem, const int item, const int vh) {
;     ...
;             for (int ks = 0; ks < 4; ++ks) { const f32x4 n0 = *(const f32x4*)(n_s + ks * 32 + kq * 8), n1 = *(const f32x4*)(n_s + ks * 32 + kq * 8 + 4);
;                 const u32x4 qw = *(const u32x4*)&qf[ks];
;                 nq += bflo(qw.x) * n0[0] + bfhi(qw.x) * n0[1] + bflo(qw.y) * n0[2] + bfhi(qw.y) * n0[3] + bflo(qw.z) * n1[0] + bfhi(qw.z) * n1[1] + bflo(qw.w) * n1[2] + bfhi(qw.w) * n1[3]; }
;             rs += __shfl_xor(rs, 16); rs += __shfl_xor(rs, 32); nq += __shfl_xor(nq, 16); nq += __shfl_xor(nq, 32);
;             const float exl = __expf(m_old - Ml);
;             const float den = rs + exl * nq;
;             const float hinv = __builtin_amdgcn_rcpf(fmaxf(fabsf(den), __expf(-(gl + Ml))));
;             __syncthreads();
; #pragma unroll
;             for (int nb = 0; nb < 8; ++nb) *(u32x2*)(KP + swz(l, nb * 2 + (kq >> 1)) + (kq & 1) * 8) = pp[nb];
;             f32x4 acc2[NBV];
; #pragma unroll
;             for (int nb = 0; nb < NBV; ++nb) acc2[nb] = (f32x4){0.f, 0.f, 0.f, 0.f};
;             __builtin_amdgcn_sched_barrier(0);
;             mm16<NBV>(acc2, CS + vh * 16384, qf, lane);
	v_pk_fma_f32 v[152:153], v[160:161], v[154:155], v[152:153]
	v_mul_f32_e32 v154, v161, v155
	v_pk_add_f32 v[160:161], v[154:155], v[152:153] op_sel_hi:[0,1]
	ds_read_b128 v[152:155], v137 offset:384
	ds_read_b128 v[164:167], v137 offset:400
	v_and_b32_e32 v199, 0xffff0000, v12
	v_lshlrev_b32_e32 v198, 16, v12
	v_and_b32_e32 v197, 0xffff0000, v23
	s_waitcnt lgkmcnt(1)
	v_mul_f32_e32 v158, v153, v199
	v_pk_fma_f32 v[152:153], v[152:153], v[198:199], v[158:159] op_sel_hi:[1,1,0]
	v_and_b32_e32 v199, 0xffff0000, v13
	v_lshlrev_b32_e32 v198, 16, v13
	v_pk_fma_f32 v[152:153], v[154:155], v[198:199], v[152:153]
	v_mul_f32_e32 v154, v155, v199
	v_pk_add_f32 v[152:153], v[154:155], v[152:153] op_sel_hi:[0,1]
	v_and_b32_e32 v155, 0xffff0000, v14
	v_lshlrev_b32_e32 v154, 16, v14
	s_waitcnt lgkmcnt(0)
	v_pk_fma_f32 v[152:153], v[164:165], v[154:155], v[152:153]
	v_mul_f32_e32 v154, v165, v155
	v_pk_add_f32 v[164:165], v[182:183], v[180:181]
	v_pk_add_f32 v[152:153], v[154:155], v[152:153] op_sel_hi:[0,1]
	v_pk_add_f32 v[164:165], v[184:185], v[164:165]
	v_and_b32_e32 v155, 0xffff0000, v15
	v_lshlrev_b32_e32 v154, 16, v15
	v_pk_add_f32 v[164:165], v[188:189], v[164:165]
	v_lshlrev_b32_e32 v196, 16, v23
	v_pk_fma_f32 v[152:153], v[166:167], v[154:155], v[152:153]
	v_and_b32_e32 v154, 64, v150
	v_pk_add_f32 v[164:165], v[172:173], v[164:165]
	v_pk_fma_f32 v[160:161], v[162:163], v[196:197], v[160:161]
	v_add_u32_e32 v162, 64, v154
	v_pk_add_f32 v[164:165], v[190:191], v[164:165]
	v_mul_f32_e32 v154, v159, v195
	v_pk_add_f32 v[164:165], v[174:175], v[164:165]
	v_pk_add_f32 v[156:157], v[154:155], v[156:157] op_sel_hi:[0,1]
	v_mul_f32_e32 v154, v163, v197
	v_xor_b32_e32 v87, 16, v150
	v_pk_add_f32 v[164:165], v[66:67], v[164:165]
	v_mov_b32_e32 v157, v177
	v_pk_add_f32 v[158:159], v[154:155], v[160:161] op_sel_hi:[0,1]
	v_mul_f32_e32 v154, v167, v155
	v_cmp_lt_i32_e32 vcc, v87, v162
	v_pk_add_f32 v[156:157], v[156:157], v[164:165]
	v_mov_b32_e32 v159, v200
	v_pk_add_f32 v[152:153], v[154:155], v[152:153] op_sel_hi:[0,1]
	v_cndmask_b32_e32 v87, v150, v87, vcc
	v_pk_add_f32 v[156:157], v[158:159], v[156:157]
	v_mov_b32_e32 v153, v201
	v_lshlrev_b32_e32 v87, 2, v87
	v_pk_add_f32 v[152:153], v[152:153], v[156:157]
	ds_bpermute_b32 v155, v87, v153
	ds_bpermute_b32 v154, v87, v152
	v_xor_b32_e32 v67, 32, v150
	v_cmp_lt_i32_e32 vcc, v67, v162
	v_sub_f32_e32 v86, v86, v171
	v_mul_f32_e32 v86, 0x3fb8aa3b, v86
	v_cndmask_b32_e32 v67, v150, v67, vcc
	v_lshlrev_b32_e32 v67, 2, v67
	s_waitcnt lgkmcnt(0)
	v_pk_add_f32 v[152:153], v[152:153], v[154:155]
	ds_bpermute_b32 v155, v67, v153
	ds_bpermute_b32 v154, v67, v152
	v_add_f32_e32 v151, v171, v151
	v_exp_f32_e32 v86, v86
	v_mul_f32_e32 v151, 0xbfb8aa3b, v151
	v_exp_f32_e32 v151, v151
	s_waitcnt lgkmcnt(0)
	v_pk_add_f32 v[152:153], v[152:153], v[154:155]
	s_nop 0
	v_fmac_f32_e32 v153, v86, v152
	v_max_f32_e64 v151, |v153|, v151
	s_barrier
	ds_write_b64 v138, v[88:89]
	ds_write_b64 v139, v[90:91]
	ds_write_b64 v140, v[92:93]
	ds_write_b64 v141, v[94:95]
	ds_write_b64 v142, v[168:169]
	ds_write_b64 v143, v[186:187]
	ds_write_b64 v144, v[192:193]
	ds_write_b64 v145, v[178:179]
	v_add_u32_e32 v156, s89, v107
	ds_read_b128 v[88:91], v156
	ds_read_b128 v[92:95], v156 offset:4096
	ds_read_b128 v[152:155], v156 offset:8192
	ds_read_b128 v[156:159], v156 offset:12288
	s_waitcnt lgkmcnt(3)
	v_mfma_f32_16x16x32_bf16 v[88:91], v[88:91], v[28:31], 0
	s_waitcnt lgkmcnt(2)
	v_mfma_f32_16x16x32_bf16 v[92:95], v[92:95], v[28:31], 0
	s_waitcnt lgkmcnt(1)
	v_mfma_f32_16x16x32_bf16 v[152:155], v[152:155], v[28:31], 0
	s_waitcnt lgkmcnt(0)
	v_mfma_f32_16x16x32_bf16 v[28:31], v[156:159], v[28:31], 0
	v_add_u32_e32 v249, s89, v109
	ds_read_b128 v[218:221], v249
	ds_read_b128 v[222:225], v249 offset:4096
	ds_read_b128 v[226:229], v249 offset:8192
	ds_read_b128 v[230:233], v249 offset:12288
	v_add_u32_e32 v160, s89, v109
	s_nop 0
	s_waitcnt lgkmcnt(3)
	v_mfma_f32_16x16x32_bf16 v[88:91], v[218:221], v[24:27], v[88:91]
	s_nop 0
	s_waitcnt lgkmcnt(2)
	v_mfma_f32_16x16x32_bf16 v[92:95], v[222:225], v[24:27], v[92:95]
	s_nop 0
	s_waitcnt lgkmcnt(1)
	v_mfma_f32_16x16x32_bf16 v[152:155], v[226:229], v[24:27], v[152:155]
	s_nop 0
	s_waitcnt lgkmcnt(0)
	v_mfma_f32_16x16x32_bf16 v[24:27], v[230:233], v[24:27], v[28:31]
	v_add_u32_e32 v156, s89, v111
	s_nop 1
	ds_read_b128 v[28:31], v156
	s_waitcnt lgkmcnt(0)
	v_mfma_f32_16x16x32_bf16 v[28:31], v[28:31], v[20:23], v[88:91]
	s_nop 2
	ds_read_b128 v[88:91], v156 offset:4096
	s_waitcnt lgkmcnt(0)
	v_mfma_f32_16x16x32_bf16 v[88:91], v[88:91], v[20:23], v[92:95]
	s_nop 2
	ds_read_b128 v[92:95], v156 offset:8192
	s_waitcnt lgkmcnt(0)
	v_mfma_f32_16x16x32_bf16 v[92:95], v[92:95], v[20:23], v[152:155]
	s_nop 2
	ds_read_b128 v[152:155], v156 offset:12288
	s_waitcnt lgkmcnt(0)
	v_mfma_f32_16x16x32_bf16 v[20:23], v[152:155], v[20:23], v[24:27]
	v_add_u32_e32 v156, s89, v113
	s_nop 1
	ds_read_b128 v[226:229], v156
	ds_read_b128 v[230:233], v156 offset:4096
	ds_read_b128 v[234:237], v156 offset:8192
	ds_read_b128 v[24:27], v156 offset:12288
	s_waitcnt lgkmcnt(3)
	v_mfma_f32_16x16x32_bf16 v[152:155], v[226:229], v[12:15], v[28:31]
	s_nop 0
	s_waitcnt lgkmcnt(2)
	v_mfma_f32_16x16x32_bf16 v[88:91], v[230:233], v[12:15], v[88:91]
	s_nop 0
	s_waitcnt lgkmcnt(1)
	v_mfma_f32_16x16x32_bf16 v[92:95], v[234:237], v[12:15], v[92:95]
	s_nop 0
	s_waitcnt lgkmcnt(0)
; __device__ __forceinline__ unsigned cvt_pk(float lo, float hi) { unsigned r; asm volatile("v_cvt_pk_bf16_f32 %0, %1, %2" : "=v"(r) : "v"(lo), "v"(hi)); return r; }
; #define Q_LOAD(j) do { const size_t r = (size_t)(rfirst + rstep * ((j) * 128 + wid * 16 + li)); \
;           _Pragma("unroll") for (int ks = 0; ks < 4; ++ks) qf[ks] = *(const bf16x8*)(Q0 + r * 512 + h * 128 + ks * 32 + kq * 8); } while (0)
; template <int SPLIT> __device__ __forceinline__ void scan_item(const Params& p, unsigned char* smem, const int item, const int vh) {
;     ...
;             mm16<NBV>(acc2, CS + vh * 16384, qf, lane);
;             __builtin_amdgcn_sched_barrier(0);
;             Q_LOAD(jn);
; #pragma unroll
;             for (int nb = 0; nb < NBV; ++nb) acc2[nb] *= exl;
;             __builtin_amdgcn_sched_barrier(0);
;             { bf16x8 pf[4]; ldfrag(pf, KP, wid, lane); mm16<NBV>(acc2, VT + vh * 16384, pf, lane); }
;             __builtin_amdgcn_sched_barrier(0);
;             { bf16_t* hp = P0 + rowl * LDP + dir * 512 + h * 128 + vh * 64 + kq * 4;
; #pragma unroll
;               for (int nb = 0; nb < NBV; ++nb) { u32x2 o; o.x = cvt_pk(acc2[nb][0] * hinv, acc2[nb][1] * hinv); o.y = cvt_pk(acc2[nb][2] * hinv, acc2[nb][3] * hinv);
;                   *(u32x2*)(hp + nb * 16) = o; } }
;             __builtin_amdgcn_sched_barrier(0);
;             float nnew;
;             { bf16x8 vf[4]; ldfrag(vf, VT, vblk, lane);
; #pragma unroll
;               for (int nb = 0; nb < NBV; ++nb) Cacc[nb] *= decay;
;               mm16<NBV>(Cacc, KT + kh * 16384, vf, lane);
	v_mfma_f32_16x16x32_bf16 v[156:159], v[24:27], v[12:15], v[20:23]
	s_nop 0
	v_add_u32_e32 v12, s0, v96
	v_mul_lo_u32 v12, v12, s3
	v_add_u32_e32 v12, s33, v12
	v_ashrrev_i32_e32 v13, 31, v12
	v_lshlrev_b64 v[12:13], 10, v[12:13]
	v_lshl_add_u64 v[12:13], v[76:77], 0, v[12:13]
	global_load_dwordx4 v[28:31], v[12:13], off
	global_load_dwordx4 v[24:27], v[12:13], off offset:64
	global_load_dwordx4 v[20:23], v[12:13], off offset:128
	s_nop 0
	global_load_dwordx4 v[12:15], v[12:13], off offset:192
	v_pk_mul_f32 v[154:155], v[86:87], v[154:155] op_sel_hi:[0,1]
	v_pk_mul_f32 v[152:153], v[86:87], v[152:153] op_sel_hi:[0,1]
	v_pk_mul_f32 v[90:91], v[86:87], v[90:91] op_sel_hi:[0,1]
	v_pk_mul_f32 v[88:89], v[86:87], v[88:89] op_sel_hi:[0,1]
	v_pk_mul_f32 v[94:95], v[86:87], v[94:95] op_sel_hi:[0,1]
	v_rcp_f32_e32 v151, v151
	v_pk_mul_f32 v[92:93], v[86:87], v[92:93] op_sel_hi:[0,1]
	v_pk_mul_f32 v[158:159], v[86:87], v[158:159] op_sel_hi:[0,1]
	v_pk_mul_f32 v[156:157], v[86:87], v[156:157] op_sel_hi:[0,1]
	v_add_u32_e32 v86, s90, v107
	ds_read_b128 v[160:163], v86 offset:32768
	v_add_u32_e32 v164, v115, v114
	ds_read_b128 v[164:167], v164
	ds_read_b128 v[172:175], v86 offset:36864
	v_add_u32_e32 v168, v116, v114
	ds_read_b128 v[178:181], v168
	s_waitcnt lgkmcnt(1)
	v_mfma_f32_16x16x32_bf16 v[88:91], v[172:175], v[164:167], v[88:91]
	v_add_u32_e32 v168, v118, v114
	ds_read_b128 v[172:175], v86 offset:45056
	v_mfma_f32_16x16x32_bf16 v[152:155], v[160:163], v[164:167], v[152:155]
	ds_read_b128 v[160:163], v86 offset:40960
	v_add_u32_e32 v86, v117, v114
	s_waitcnt lgkmcnt(0)
	v_mfma_f32_16x16x32_bf16 v[92:95], v[160:163], v[164:167], v[92:95]
	ds_read_b128 v[160:163], v86
	ds_read_b128 v[182:185], v168
	v_mfma_f32_16x16x32_bf16 v[156:159], v[172:175], v[164:167], v[156:159]
	v_add_u32_e32 v86, s90, v109
	ds_read_b128 v[226:229], v86 offset:32768
	ds_read_b128 v[230:233], v86 offset:36864
	ds_read_b128 v[234:237], v86 offset:40960
	ds_read_b128 v[164:167], v86 offset:45056
	s_waitcnt lgkmcnt(3)
	v_mfma_f32_16x16x32_bf16 v[152:155], v[226:229], v[178:181], v[152:155]
	s_nop 0
	s_waitcnt lgkmcnt(2)
	v_mfma_f32_16x16x32_bf16 v[88:91], v[230:233], v[178:181], v[88:91]
	s_nop 0
	s_waitcnt lgkmcnt(1)
	v_mfma_f32_16x16x32_bf16 v[92:95], v[234:237], v[178:181], v[92:95]
	s_nop 0
	s_waitcnt lgkmcnt(0)
	v_mfma_f32_16x16x32_bf16 v[156:159], v[164:167], v[178:181], v[156:159]
	s_nop 0
	v_add_u32_e32 v86, s90, v111
	ds_read_b128 v[226:229], v86 offset:32768
	ds_read_b128 v[230:233], v86 offset:36864
	ds_read_b128 v[234:237], v86 offset:40960
	ds_read_b128 v[164:167], v86 offset:45056
	s_waitcnt lgkmcnt(3)
	v_mfma_f32_16x16x32_bf16 v[152:155], v[226:229], v[160:163], v[152:155]
	s_nop 0
	s_waitcnt lgkmcnt(2)
	v_mfma_f32_16x16x32_bf16 v[88:91], v[230:233], v[160:163], v[88:91]
	s_nop 0
	s_waitcnt lgkmcnt(1)
	v_mfma_f32_16x16x32_bf16 v[92:95], v[234:237], v[160:163], v[92:95]
	s_nop 0
	s_waitcnt lgkmcnt(0)
	v_mfma_f32_16x16x32_bf16 v[156:159], v[164:167], v[160:163], v[156:159]
	s_nop 0
	v_add_u32_e32 v250, s90, v113
	ds_read_b128 v[218:221], v250 offset:32768
	ds_read_b128 v[222:225], v250 offset:36864
	ds_read_b128 v[226:229], v250 offset:40960
	ds_read_b128 v[230:233], v250 offset:45056
	v_add_u32_e32 v86, s90, v113
	s_nop 0
	s_waitcnt lgkmcnt(3)
	v_mfma_f32_16x16x32_bf16 v[152:155], v[218:221], v[182:185], v[152:155]
	s_nop 0
	s_waitcnt lgkmcnt(2)
	v_mfma_f32_16x16x32_bf16 v[88:91], v[222:225], v[182:185], v[88:91]
	s_nop 0
	s_waitcnt lgkmcnt(1)
	v_mfma_f32_16x16x32_bf16 v[92:95], v[226:229], v[182:185], v[92:95]
	s_nop 0
	s_waitcnt lgkmcnt(0)
	v_mfma_f32_16x16x32_bf16 v[156:159], v[230:233], v[182:185], v[156:159]
	v_mul_f32_e32 v86, v151, v152
	v_mul_f32_e32 v152, v151, v153
	v_cvt_pk_bf16_f32 v152, v86, v152
	v_mul_f32_e32 v86, v151, v154
	v_mul_f32_e32 v153, v151, v155
	v_mad_i64_i32 v[160:161], s[4:5], v131, s88, v[78:79]
	v_cvt_pk_bf16_f32 v153, v86, v153
	v_mul_f32_e32 v86, v151, v88
	v_mul_f32_e32 v88, v151, v89
	global_store_dwordx2 v[160:161], v[152:153], off
	v_cvt_pk_bf16_f32 v88, v86, v88
	v_mul_f32_e32 v86, v151, v90
	v_mul_f32_e32 v89, v151, v91
	v_cvt_pk_bf16_f32 v89, v86, v89
	global_store_dwordx2 v[160:161], v[88:89], off offset:32
	v_mul_f32_e32 v86, v151, v92
	v_mul_f32_e32 v88, v151, v93
	v_cvt_pk_bf16_f32 v88, v86, v88
	v_mul_f32_e32 v86, v151, v94
	v_mul_f32_e32 v89, v151, v95
	v_cvt_pk_bf16_f32 v89, v86, v89
	global_store_dwordx2 v[160:161], v[88:89], off offset:64
	v_mul_f32_e32 v86, v151, v156
	v_mul_f32_e32 v88, v151, v157
	v_cvt_pk_bf16_f32 v88, v86, v88
	v_mul_f32_e32 v86, v151, v158
	v_mul_f32_e32 v89, v151, v159
	v_cvt_pk_bf16_f32 v89, v86, v89
	global_store_dwordx2 v[160:161], v[88:89], off offset:96
	v_add_u32_e32 v86, v120, v107
	ds_read_b128 v[88:91], v86
	v_add_u32_e32 v92, v115, v119
	ds_read_b128 v[92:95], v92 offset:32768
	ds_read_b128 v[152:155], v86 offset:4096
	v_add_u32_e32 v151, v116, v119
	v_pk_mul_f32 v[50:51], v[50:51], v[84:85] op_sel_hi:[1,0]
	v_pk_mul_f32 v[48:49], v[48:49], v[84:85] op_sel_hi:[1,0]
	ds_read_b128 v[156:159], v151 offset:32768
	ds_read_b128 v[160:163], v86 offset:8192
	v_add_u32_e32 v151, v117, v119
	v_pk_mul_f32 v[54:55], v[54:55], v[84:85] op_sel_hi:[1,0]
	s_waitcnt lgkmcnt(3)
	v_mfma_f32_16x16x32_bf16 v[48:51], v[88:91], v[92:95], v[48:51]
	ds_read_b128 v[88:91], v86 offset:12288
	v_pk_mul_f32 v[52:53], v[52:53], v[84:85] op_sel_hi:[1,0]
	v_pk_mul_f32 v[58:59], v[58:59], v[84:85] op_sel_hi:[1,0]
	v_pk_mul_f32 v[56:57], v[56:57], v[84:85] op_sel_hi:[1,0]
	s_waitcnt lgkmcnt(3)
; __device__ __forceinline__ unsigned cvt_pk(float lo, float hi) { unsigned r; asm volatile("v_cvt_pk_bf16_f32 %0, %1, %2" : "=v"(r) : "v"(lo), "v"(hi)); return r; }
; __device__ __forceinline__ float bflo(unsigned w) { return __uint_as_float(w << 16); }
; __device__ __forceinline__ float bfhi(unsigned w) { return __uint_as_float(w & 0xffff0000u); }
; template <int SPLIT> __device__ __forceinline__ void scan_item(const Params& p, unsigned char* smem, const int item, const int vh) {
;     ...
;               float part = 0.f;
; #pragma unroll
;               for (int ks = 0; ks < 4; ++ks) { const u32x4 kw = *(const u32x4*)(KT + swz(wid * 16 + li, ks * 4 + kq));
;                   part += bflo(kw.x) + bfhi(kw.x) + bflo(kw.y) + bfhi(kw.y) + bflo(kw.z) + bfhi(kw.z) + bflo(kw.w) + bfhi(kw.w); }
;               part += __shfl_xor(part, 16); part += __shfl_xor(part, 32);
;               nnew = decay * n_s[wid * 16 + li] + part; }
;             __syncthreads();
; #pragma unroll
;             for (int nb = 0; nb < NBV; ++nb) { u32x2 o; o.x = cvt_pk(Cacc[nb][0], Cacc[nb][1]); o.y = cvt_pk(Cacc[nb][2], Cacc[nb][3]);
;                 *(u32x2*)(CS + swz(vblk * 16 + li, (kh * 4 + nb) * 2 + (kq >> 1)) + (kq & 1) * 8) = o; }
;             if (kq == 0) n_s[wid * 16 + li] = nnew;
	v_mfma_f32_16x16x32_bf16 v[52:55], v[152:155], v[92:95], v[52:55]
	v_add_u32_e32 v86, v118, v119
	v_pk_mul_f32 v[62:63], v[62:63], v[84:85] op_sel_hi:[1,0]
	v_pk_mul_f32 v[60:61], v[60:61], v[84:85] op_sel_hi:[1,0]
	s_waitcnt lgkmcnt(1)
	v_mfma_f32_16x16x32_bf16 v[56:59], v[160:163], v[92:95], v[56:59]
	ds_read_b128 v[152:155], v151 offset:32768
	ds_read_b128 v[160:163], v86 offset:32768
	s_waitcnt lgkmcnt(2)
	v_mfma_f32_16x16x32_bf16 v[60:63], v[88:91], v[92:95], v[60:63]
	v_add_u32_e32 v251, v120, v109
	ds_read_b128 v[218:221], v251
	ds_read_b128 v[222:225], v251 offset:4096
	ds_read_b128 v[226:229], v251 offset:8192
	ds_read_b128 v[230:233], v251 offset:12288
	v_add_u32_e32 v252, v120, v111
	ds_read_b128 v[234:237], v252
	v_add_u32_e32 v86, v120, v109
	ds_read_b128 v[238:241], v252 offset:4096
	s_waitcnt lgkmcnt(5)
	v_mfma_f32_16x16x32_bf16 v[48:51], v[218:221], v[156:159], v[48:51]
	ds_read_b128 v[218:221], v252 offset:8192
	s_waitcnt lgkmcnt(5)
	v_mfma_f32_16x16x32_bf16 v[52:55], v[222:225], v[156:159], v[52:55]
	ds_read_b128 v[222:225], v252 offset:12288
	s_waitcnt lgkmcnt(5)
	v_mfma_f32_16x16x32_bf16 v[56:59], v[226:229], v[156:159], v[56:59]
	v_add_u32_e32 v253, v120, v113
	ds_read_b128 v[226:229], v253
	s_waitcnt lgkmcnt(5)
	v_mfma_f32_16x16x32_bf16 v[60:63], v[230:233], v[156:159], v[60:63]
	v_add_u32_e32 v86, v120, v111
	ds_read_b128 v[230:233], v253 offset:4096
	s_waitcnt lgkmcnt(5)
	v_mfma_f32_16x16x32_bf16 v[48:51], v[234:237], v[152:155], v[48:51]
	ds_read_b128 v[234:237], v253 offset:8192
	s_waitcnt lgkmcnt(5)
	v_mfma_f32_16x16x32_bf16 v[52:55], v[238:241], v[152:155], v[52:55]
	ds_read_b128 v[238:241], v253 offset:12288
	s_waitcnt lgkmcnt(5)
	v_mfma_f32_16x16x32_bf16 v[56:59], v[218:221], v[152:155], v[56:59]
	s_nop 0
	s_waitcnt lgkmcnt(4)
	v_mfma_f32_16x16x32_bf16 v[60:63], v[222:225], v[152:155], v[60:63]
	v_add_u32_e32 v86, v120, v113
	s_nop 0
	s_waitcnt lgkmcnt(3)
	v_mfma_f32_16x16x32_bf16 v[48:51], v[226:229], v[160:163], v[48:51]
	s_nop 0
	s_waitcnt lgkmcnt(2)
	v_mfma_f32_16x16x32_bf16 v[52:55], v[230:233], v[160:163], v[52:55]
	s_nop 0
	s_waitcnt lgkmcnt(1)
	v_mfma_f32_16x16x32_bf16 v[56:59], v[234:237], v[160:163], v[56:59]
	s_nop 0
	s_waitcnt lgkmcnt(0)
	v_mfma_f32_16x16x32_bf16 v[60:63], v[238:241], v[160:163], v[60:63]
	v_add_u32_e32 v86, v121, v106
	v_add_u32_e32 v242, v121, v108
	v_add_u32_e32 v243, v121, v110
	v_add_u32_e32 v244, v121, v112
	ds_read_b128 v[88:91], v86
	ds_read_b128 v[246:249], v242
	ds_read_b128 v[250:253], v243
	ds_read_b128 v[218:221], v244
	s_waitcnt lgkmcnt(3)
	v_lshlrev_b32_e32 v86, 16, v88
	v_and_b32_e32 v88, 0xffff0000, v88
	v_add_f32_e32 v86, v86, v88
	v_lshlrev_b32_e32 v88, 16, v89
	v_add_f32_e32 v86, v86, v88
	v_and_b32_e32 v88, 0xffff0000, v89
	v_add_f32_e32 v86, v86, v88
	v_lshlrev_b32_e32 v88, 16, v90
	v_add_f32_e32 v86, v86, v88
	v_and_b32_e32 v88, 0xffff0000, v90
	v_add_f32_e32 v86, v86, v88
	v_lshlrev_b32_e32 v88, 16, v91
	v_add_f32_e32 v86, v86, v88
	v_and_b32_e32 v88, 0xffff0000, v91
	v_add_f32_e32 v86, v86, v88
	v_add_f32_e32 v86, 0, v86
	s_waitcnt lgkmcnt(2)
	v_lshlrev_b32_e32 v92, 16, v246
	v_and_b32_e32 v88, 0xffff0000, v246
	v_add_f32_e32 v88, v92, v88
	v_lshlrev_b32_e32 v92, 16, v247
	v_add_f32_e32 v88, v88, v92
	v_and_b32_e32 v89, 0xffff0000, v247
	v_add_f32_e32 v88, v88, v89
	v_lshlrev_b32_e32 v89, 16, v248
	v_add_f32_e32 v88, v88, v89
	v_and_b32_e32 v89, 0xffff0000, v248
	v_add_f32_e32 v88, v88, v89
	v_lshlrev_b32_e32 v89, 16, v249
	v_add_f32_e32 v88, v88, v89
	v_and_b32_e32 v89, 0xffff0000, v249
	v_add_f32_e32 v88, v88, v89
	v_add_f32_e32 v86, v86, v88
	s_waitcnt lgkmcnt(1)
	v_lshlrev_b32_e32 v92, 16, v250
	v_and_b32_e32 v88, 0xffff0000, v250
	v_add_f32_e32 v88, v92, v88
	v_lshlrev_b32_e32 v92, 16, v251
	v_add_f32_e32 v88, v88, v92
	v_and_b32_e32 v89, 0xffff0000, v251
	v_add_f32_e32 v88, v88, v89
	v_lshlrev_b32_e32 v89, 16, v252
	v_add_f32_e32 v88, v88, v89
	v_and_b32_e32 v89, 0xffff0000, v252
	v_add_f32_e32 v88, v88, v89
	v_lshlrev_b32_e32 v89, 16, v253
	v_add_f32_e32 v88, v88, v89
	v_and_b32_e32 v89, 0xffff0000, v253
	v_add_f32_e32 v88, v88, v89
	v_add_f32_e32 v86, v86, v88
	s_waitcnt lgkmcnt(0)
	v_lshlrev_b32_e32 v92, 16, v218
	v_and_b32_e32 v88, 0xffff0000, v218
	v_add_f32_e32 v88, v92, v88
	v_lshlrev_b32_e32 v92, 16, v219
	v_add_f32_e32 v88, v88, v92
	v_and_b32_e32 v89, 0xffff0000, v219
	v_add_f32_e32 v88, v88, v89
	v_lshlrev_b32_e32 v89, 16, v220
	v_add_f32_e32 v88, v88, v89
	v_and_b32_e32 v89, 0xffff0000, v220
	v_add_f32_e32 v88, v88, v89
	v_lshlrev_b32_e32 v89, 16, v221
	v_add_f32_e32 v88, v88, v89
	v_and_b32_e32 v89, 0xffff0000, v221
	v_add_f32_e32 v88, v88, v89
	v_add_f32_e32 v86, v86, v88
	ds_bpermute_b32 v87, v87, v86
	s_waitcnt lgkmcnt(0)
	v_add_f32_e32 v86, v86, v87
	ds_bpermute_b32 v67, v67, v86
	ds_read_b32 v87, v122
	s_waitcnt lgkmcnt(0)
	s_barrier
	v_cvt_pk_bf16_f32 v88, v48, v49
	v_cvt_pk_bf16_f32 v89, v50, v51
	ds_write_b64 v146, v[88:89]
	v_cvt_pk_bf16_f32 v88, v52, v53
	v_cvt_pk_bf16_f32 v89, v54, v55
	ds_write_b64 v147, v[88:89]
	v_cvt_pk_bf16_f32 v88, v56, v57
	v_cvt_pk_bf16_f32 v89, v58, v59
	ds_write_b64 v148, v[88:89]
	v_cvt_pk_bf16_f32 v88, v60, v61
	v_cvt_pk_bf16_f32 v89, v62, v63
	ds_write_b64 v149, v[88:89]
	s_and_saveexec_b64 s[86:87], s[8:9]
	s_cbranch_execz .LBB0_311
	v_add_f32_e32 v67, v86, v67
	v_fmac_f32_e32 v67, v84, v87
	ds_write_b32 v122, v67
	s_branch .LBB0_311
